# P1 tile prologue: adaLN partial sums requested together, one wait
# speedup vs baseline: 1.0041x; 1.0023x over previous
.LBB0_266:
	v_ashrrev_i32_e32 v9, 31, v3
	v_mov_b32_e32 v8, v3
	v_ashrrev_i32_e32 v11, 31, v2
	v_mov_b32_e32 v10, v2
	v_lshlrev_b64 v[10:11], 2, v[10:11]
	v_lshlrev_b64 v[8:9], 2, v[8:9]
	v_add_u32_e32 v3, 0x400, v3
	v_add_u32_e32 v2, 0x400, v2
	v_lshl_add_u64 v[216:217], s[8:9], 0, v[10:11]
	v_lshl_add_u64 v[218:219], s[8:9], 0, v[8:9]
	global_load_dword v12, v[216:217], off
	global_load_dword v13, v[218:219], off
	v_ashrrev_i32_e32 v217, 31, v2
	v_mov_b32_e32 v216, v2
	v_ashrrev_i32_e32 v219, 31, v3
	v_mov_b32_e32 v218, v3
	v_lshl_add_u64 v[216:217], v[216:217], 2, s[8:9]
	v_lshl_add_u64 v[218:219], v[218:219], 2, s[8:9]
	global_load_dword v16, v[216:217], off
	global_load_dword v17, v[218:219], off
	v_lshl_add_u64 v[216:217], s[58:59], 0, v[10:11]
	v_lshl_add_u64 v[218:219], s[58:59], 0, v[8:9]
	global_load_dword v14, v[216:217], off
	global_load_dword v15, v[218:219], off
	v_lshl_add_u64 v[216:217], s[60:61], 0, v[10:11]
	v_lshl_add_u64 v[218:219], s[60:61], 0, v[8:9]
	global_load_dword v200, v[216:217], off
	global_load_dword v201, v[218:219], off
	v_lshl_add_u64 v[216:217], s[62:63], 0, v[10:11]
	v_lshl_add_u64 v[218:219], s[62:63], 0, v[8:9]
	global_load_dword v202, v[216:217], off
	global_load_dword v203, v[218:219], off
	v_lshl_add_u64 v[216:217], s[64:65], 0, v[10:11]
	v_lshl_add_u64 v[218:219], s[64:65], 0, v[8:9]
	global_load_dword v204, v[216:217], off
	global_load_dword v205, v[218:219], off
	v_lshl_add_u64 v[216:217], s[66:67], 0, v[10:11]
	v_lshl_add_u64 v[218:219], s[66:67], 0, v[8:9]
	global_load_dword v206, v[216:217], off
	global_load_dword v207, v[218:219], off
	v_lshl_add_u64 v[216:217], s[68:69], 0, v[10:11]
	v_lshl_add_u64 v[218:219], s[68:69], 0, v[8:9]
	global_load_dword v208, v[216:217], off
	global_load_dword v209, v[218:219], off
	v_lshl_add_u64 v[216:217], s[70:71], 0, v[10:11]
	v_lshl_add_u64 v[218:219], s[70:71], 0, v[8:9]
	global_load_dword v210, v[216:217], off
	global_load_dword v211, v[218:219], off
	v_lshl_add_u64 v[216:217], s[72:73], 0, v[10:11]
	v_lshl_add_u64 v[218:219], s[72:73], 0, v[8:9]
	global_load_dword v212, v[216:217], off
	global_load_dword v213, v[218:219], off
	v_lshl_add_u64 v[216:217], s[10:11], 0, v[10:11]
	v_lshl_add_u64 v[218:219], s[10:11], 0, v[8:9]
	global_load_dword v214, v[216:217], off
	global_load_dword v215, v[218:219], off
	v_add_u32_e32 v7, -2, v7
	v_cmp_eq_u32_e32 vcc, 0, v7
	s_or_b64 s[74:75], vcc, s[74:75]
	s_waitcnt vmcnt(0)
	v_pk_add_f32 v[12:13], v[12:13], v[14:15]
	v_pk_add_f32 v[14:15], v[16:17], v[200:201]
	v_pk_add_f32 v[12:13], v[12:13], v[202:203]
	v_pk_add_f32 v[14:15], v[14:15], v[204:205]
	v_pk_add_f32 v[12:13], v[12:13], v[206:207]
	v_pk_add_f32 v[14:15], v[14:15], v[208:209]
	v_pk_add_f32 v[12:13], v[12:13], v[210:211]
	v_pk_add_f32 v[14:15], v[14:15], v[212:213]
	s_nop 0
	v_pk_add_f32 v[8:9], v[14:15], 1.0 op_sel_hi:[1,0]
	s_nop 0
	v_pk_mul_f32 v[8:9], v[214:215], v[8:9]
	ds_write2st64_b32 v6, v8, v9 offset1:8
	v_lshl_add_u32 v8, v2, 2, 0
	v_add_u32_e32 v6, 0x1000, v6
	v_lshl_add_u32 v9, v3, 2, 0
	ds_write_b32 v8, v12
	ds_write_b32 v9, v13
	s_andn2_b64 exec, exec, s[74:75]
	s_cbranch_execnz .LBB0_266
	s_or_b64 exec, exec, s[74:75]
	v_cmp_ne_u32_e32 vcc, v4, v5
	v_lshl_add_u32 v2, v5, 9, v66
	s_orn2_b64 s[58:59], vcc, exec
